# d4 + hot loop heads (8 GEMM K-loops, 2 attention loops) padded with s_nop to 64-byte alignment
# speedup vs baseline: 1.0136x; 1.0071x over previous
; template <class Epi>
; __device__ __forceinline__ void gemm_phase(LAS unsigned char* lds, const Gemm g, const StaticOrder& S, const Epi& E) {
;     ...
;     for (;;) {
;         const bool has_next = S.next(ui + 1, nxt);
;         const char* nA = has_next ? (const char*)g.A + (size_t)nxt.pm * tstep : cA; const char* nB = has_next ? (const char*)g.Bt + (size_t)nxt.pn * tstep : cB;
;     ...
; #pragma unroll
;         for (int a = 0; a < 2; ++a)
; #pragma unroll
;             for (int b = 0; b < 2; ++b)
; #pragma unroll
;                 for (int m = 0; m < 4; ++m)
; #pragma unroll
;                     for (int n = 0; n < 2; ++n) acc[a][b][m][n] = (f32x4){0.f, 0.f, 0.f, 0.f};
.LBB0_133:
	s_ashr_i32 s49, s48, 31
	s_lshl_b64 s[50:51], s[48:49], 19
	s_add_u32 s50, s34, s50
	s_addc_u32 s51, s35, s51
	s_and_b64 s[58:59], s[2:3], exec
	s_cselect_b32 s87, s51, s65
	s_cselect_b32 s88, s50, s64
	s_ashr_i32 s47, s46, 31
	s_lshl_b64 s[58:59], s[46:47], 19
	s_add_u32 s58, s33, s58
	s_addc_u32 s59, s76, s59
	s_and_b64 s[68:69], s[2:3], exec
	s_cselect_b32 s47, s59, s67
	s_cselect_b32 s89, s58, s66
	s_add_u32 s64, s64, 0x40080
	s_addc_u32 s65, s65, 0
	s_add_u32 s90, s66, 0x100
	v_mov_b32_e32 v2, 0
	s_addc_u32 s91, s67, 0
	s_mov_b32 s92, -2
	v_mov_b32_e32 v3, v2
	v_mov_b32_e32 v4, v2
	v_mov_b32_e32 v5, v2
	v_mov_b32_e32 v10, v2
	v_mov_b32_e32 v11, v2
	v_mov_b32_e32 v12, v2
	v_mov_b32_e32 v13, v2
	v_mov_b32_e32 v18, v2
	v_mov_b32_e32 v19, v2
	v_mov_b32_e32 v20, v2
	v_mov_b32_e32 v21, v2
	v_mov_b32_e32 v26, v2
	v_mov_b32_e32 v27, v2
	v_mov_b32_e32 v28, v2
	v_mov_b32_e32 v29, v2
	v_mov_b32_e32 v34, v2
	v_mov_b32_e32 v35, v2
	v_mov_b32_e32 v36, v2
	v_mov_b32_e32 v37, v2
	v_mov_b32_e32 v42, v2
	v_mov_b32_e32 v43, v2
	v_mov_b32_e32 v44, v2
	v_mov_b32_e32 v45, v2
	v_mov_b32_e32 v50, v2
	v_mov_b32_e32 v51, v2
	v_mov_b32_e32 v52, v2
	v_mov_b32_e32 v53, v2
	v_mov_b32_e32 v58, v2
	v_mov_b32_e32 v59, v2
	v_mov_b32_e32 v60, v2
	v_mov_b32_e32 v61, v2
	v_mov_b32_e32 v6, v2
	v_mov_b32_e32 v7, v2
	v_mov_b32_e32 v8, v2
	v_mov_b32_e32 v9, v2
	v_mov_b32_e32 v14, v2
	v_mov_b32_e32 v15, v2
	v_mov_b32_e32 v16, v2
	v_mov_b32_e32 v17, v2
	v_mov_b32_e32 v22, v2
	v_mov_b32_e32 v23, v2
	v_mov_b32_e32 v24, v2
	v_mov_b32_e32 v25, v2
	v_mov_b32_e32 v30, v2
	v_mov_b32_e32 v31, v2
	v_mov_b32_e32 v32, v2
	v_mov_b32_e32 v33, v2
	v_mov_b32_e32 v38, v2
	v_mov_b32_e32 v39, v2
	v_mov_b32_e32 v40, v2
	v_mov_b32_e32 v41, v2
	v_mov_b32_e32 v46, v2
	v_mov_b32_e32 v47, v2
	v_mov_b32_e32 v48, v2
	v_mov_b32_e32 v49, v2
	v_mov_b32_e32 v54, v2
	v_mov_b32_e32 v55, v2
	v_mov_b32_e32 v56, v2
	v_mov_b32_e32 v57, v2
	v_mov_b32_e32 v62, v2
	v_mov_b32_e32 v63, v2
	v_mov_b32_e32 v64, v2
	v_mov_b32_e32 v65, v2
	v_mov_b32_e32 v66, v2
	v_mov_b32_e32 v67, v2
	v_mov_b32_e32 v68, v2
	v_mov_b32_e32 v69, v2
	v_mov_b32_e32 v74, v2
	v_mov_b32_e32 v75, v2
	v_mov_b32_e32 v76, v2
	v_mov_b32_e32 v77, v2
	v_mov_b32_e32 v82, v2
	v_mov_b32_e32 v83, v2
	v_mov_b32_e32 v84, v2
	v_mov_b32_e32 v85, v2
	v_mov_b32_e32 v90, v2
	v_mov_b32_e32 v91, v2
	v_mov_b32_e32 v92, v2
	v_mov_b32_e32 v93, v2
	v_mov_b32_e32 v98, v2
	v_mov_b32_e32 v99, v2
	v_mov_b32_e32 v100, v2
	v_mov_b32_e32 v101, v2
	v_mov_b32_e32 v106, v2
	v_mov_b32_e32 v107, v2
	v_mov_b32_e32 v108, v2
	v_mov_b32_e32 v109, v2
	v_mov_b32_e32 v114, v2
	v_mov_b32_e32 v115, v2
	v_mov_b32_e32 v116, v2
	v_mov_b32_e32 v117, v2
	v_mov_b32_e32 v122, v2
	v_mov_b32_e32 v123, v2
	v_mov_b32_e32 v124, v2
	v_mov_b32_e32 v125, v2
	v_mov_b32_e32 v70, v2
	v_mov_b32_e32 v71, v2
	v_mov_b32_e32 v72, v2
	v_mov_b32_e32 v73, v2
	v_mov_b32_e32 v78, v2
	v_mov_b32_e32 v79, v2
	v_mov_b32_e32 v80, v2
	v_mov_b32_e32 v81, v2
	v_mov_b32_e32 v86, v2
	v_mov_b32_e32 v87, v2
	v_mov_b32_e32 v88, v2
	v_mov_b32_e32 v89, v2
	v_mov_b32_e32 v94, v2
	v_mov_b32_e32 v95, v2
	v_mov_b32_e32 v96, v2
	v_mov_b32_e32 v97, v2
	v_mov_b32_e32 v102, v2
	v_mov_b32_e32 v103, v2
	v_mov_b32_e32 v104, v2
	v_mov_b32_e32 v105, v2
	v_mov_b32_e32 v110, v2
	v_mov_b32_e32 v111, v2
	v_mov_b32_e32 v112, v2
	v_mov_b32_e32 v113, v2
	v_mov_b32_e32 v118, v2
	v_mov_b32_e32 v119, v2
	v_mov_b32_e32 v120, v2
	v_mov_b32_e32 v121, v2
	v_mov_b32_e32 v126, v2
	v_mov_b32_e32 v127, v2
	v_mov_b32_e32 v128, v2
	v_mov_b32_e32 v129, v2
	s_nop 0
	s_nop 0
	s_nop 0
	s_nop 0
	s_nop 0
	s_nop 0
	s_nop 0
	s_nop 0
	s_nop 0
	s_nop 0
	s_nop 0
	s_nop 0

; template <class Epi>
; __device__ __forceinline__ void gemm_phase(LAS unsigned char* lds, const Gemm g, const StaticOrder& S, const Epi& E) {
;     ...
;     for (;;) {
;         const bool has_next = S.next(ui + 1, nxt);
;         const char* nA = has_next ? (const char*)g.A + (size_t)nxt.pm * tstep : cA; const char* nB = has_next ? (const char*)g.Bt + (size_t)nxt.pn * tstep : cB;
;         for (int t = 0; t < nt; t += 2) {
;             const bool last = (t == nt - 2);
;             const char* a1 = cA + (size_t)(t + 1) * kstep;
;             const char* a2 = last ? nA : cA + (size_t)(t + 2) * kstep; const char* b2 = last ? nB : cB + (size_t)(t + 2) * kstep;
;     ...
; #pragma unroll
;         for (int a = 0; a < 2; ++a)
; #pragma unroll
;             for (int b = 0; b < 2; ++b)
; #pragma unroll
;                 for (int m = 0; m < 4; ++m)
; #pragma unroll
;                     for (int n = 0; n < 2; ++n) acc[a][b][m][n] = (f32x4){0.f, 0.f, 0.f, 0.f};
.LBB0_220:
	s_add_u32 s46, s46, 0xb0080
	s_addc_u32 s47, s47, 0
	s_add_u32 s82, s48, 0x100
	v_mov_b32_e32 v2, 0
	s_addc_u32 s83, s49, 0
	s_mov_b32 s84, -2
	s_waitcnt lgkmcnt(0)
	v_mov_b32_e32 v3, v2
	v_mov_b32_e32 v4, v2
	v_mov_b32_e32 v5, v2
	v_mov_b32_e32 v6, v2
	v_mov_b32_e32 v7, v2
	v_mov_b32_e32 v8, v2
	v_mov_b32_e32 v9, v2
	v_mov_b32_e32 v18, v2
	v_mov_b32_e32 v19, v2
	v_mov_b32_e32 v20, v2
	v_mov_b32_e32 v21, v2
	v_mov_b32_e32 v22, v2
	v_mov_b32_e32 v23, v2
	v_mov_b32_e32 v24, v2
	v_mov_b32_e32 v25, v2
	v_mov_b32_e32 v34, v2
	v_mov_b32_e32 v35, v2
	v_mov_b32_e32 v36, v2
	v_mov_b32_e32 v37, v2
	v_mov_b32_e32 v38, v2
	v_mov_b32_e32 v39, v2
	v_mov_b32_e32 v40, v2
	v_mov_b32_e32 v41, v2
	v_mov_b32_e32 v50, v2
	v_mov_b32_e32 v51, v2
	v_mov_b32_e32 v52, v2
	v_mov_b32_e32 v53, v2
	v_mov_b32_e32 v54, v2
	v_mov_b32_e32 v55, v2
	v_mov_b32_e32 v56, v2
	v_mov_b32_e32 v57, v2
	v_mov_b32_e32 v10, v2
	v_mov_b32_e32 v11, v2
	v_mov_b32_e32 v12, v2
	v_mov_b32_e32 v13, v2
	v_mov_b32_e32 v14, v2
	v_mov_b32_e32 v15, v2
	v_mov_b32_e32 v16, v2
	v_mov_b32_e32 v17, v2
	v_mov_b32_e32 v26, v2
	v_mov_b32_e32 v27, v2
	v_mov_b32_e32 v28, v2
	v_mov_b32_e32 v29, v2
	v_mov_b32_e32 v30, v2
	v_mov_b32_e32 v31, v2
	v_mov_b32_e32 v32, v2
	v_mov_b32_e32 v33, v2
	v_mov_b32_e32 v42, v2
	v_mov_b32_e32 v43, v2
	v_mov_b32_e32 v44, v2
	v_mov_b32_e32 v45, v2
	v_mov_b32_e32 v46, v2
	v_mov_b32_e32 v47, v2
	v_mov_b32_e32 v48, v2
	v_mov_b32_e32 v49, v2
	v_mov_b32_e32 v58, v2
	v_mov_b32_e32 v59, v2
	v_mov_b32_e32 v60, v2
	v_mov_b32_e32 v61, v2
	v_mov_b32_e32 v62, v2
	v_mov_b32_e32 v63, v2
	v_mov_b32_e32 v64, v2
	v_mov_b32_e32 v65, v2
	v_mov_b32_e32 v66, v2
	v_mov_b32_e32 v67, v2
	v_mov_b32_e32 v68, v2
	v_mov_b32_e32 v69, v2
	v_mov_b32_e32 v70, v2
	v_mov_b32_e32 v71, v2
	v_mov_b32_e32 v72, v2
	v_mov_b32_e32 v73, v2
	v_mov_b32_e32 v82, v2
	v_mov_b32_e32 v83, v2
	v_mov_b32_e32 v84, v2
	v_mov_b32_e32 v85, v2
	v_mov_b32_e32 v86, v2
	v_mov_b32_e32 v87, v2
	v_mov_b32_e32 v88, v2
	v_mov_b32_e32 v89, v2
	v_mov_b32_e32 v98, v2
	v_mov_b32_e32 v99, v2
	v_mov_b32_e32 v100, v2
	v_mov_b32_e32 v101, v2
	v_mov_b32_e32 v102, v2
	v_mov_b32_e32 v103, v2
	v_mov_b32_e32 v104, v2
	v_mov_b32_e32 v105, v2
	v_mov_b32_e32 v114, v2
	v_mov_b32_e32 v115, v2
	v_mov_b32_e32 v116, v2
	v_mov_b32_e32 v117, v2
	v_mov_b32_e32 v118, v2
	v_mov_b32_e32 v119, v2
	v_mov_b32_e32 v120, v2
	v_mov_b32_e32 v121, v2
	v_mov_b32_e32 v74, v2
	v_mov_b32_e32 v75, v2
	v_mov_b32_e32 v76, v2
	v_mov_b32_e32 v77, v2
	v_mov_b32_e32 v78, v2
	v_mov_b32_e32 v79, v2
	v_mov_b32_e32 v80, v2
	v_mov_b32_e32 v81, v2
	v_mov_b32_e32 v90, v2
	v_mov_b32_e32 v91, v2
	v_mov_b32_e32 v92, v2
	v_mov_b32_e32 v93, v2
	v_mov_b32_e32 v94, v2
	v_mov_b32_e32 v95, v2
	v_mov_b32_e32 v96, v2
	v_mov_b32_e32 v97, v2
	v_mov_b32_e32 v106, v2
	v_mov_b32_e32 v107, v2
	v_mov_b32_e32 v108, v2
	v_mov_b32_e32 v109, v2
	v_mov_b32_e32 v110, v2
	v_mov_b32_e32 v111, v2
	v_mov_b32_e32 v112, v2
	v_mov_b32_e32 v113, v2
	v_mov_b32_e32 v122, v2
	v_mov_b32_e32 v123, v2
	v_mov_b32_e32 v124, v2
	v_mov_b32_e32 v125, v2
	v_mov_b32_e32 v126, v2
	v_mov_b32_e32 v127, v2
	v_mov_b32_e32 v128, v2
	v_mov_b32_e32 v129, v2
	s_nop 0
	s_nop 0
	s_nop 0

; template <class Epi>
; __device__ __forceinline__ void gemm_phase(LAS unsigned char* lds, const Gemm g, const StaticOrder& S, const Epi& E) {
;     ...
;     for (;;) {
;         const bool has_next = S.next(ui + 1, nxt);
;         const char* nA = has_next ? (const char*)g.A + (size_t)nxt.pm * tstep : cA; const char* nB = has_next ? (const char*)g.Bt + (size_t)nxt.pn * tstep : cB;
;     ...
; #pragma unroll
;         for (int a = 0; a < 2; ++a)
; #pragma unroll
;             for (int b = 0; b < 2; ++b)
; #pragma unroll
;                 for (int m = 0; m < 4; ++m)
; #pragma unroll
;                     for (int n = 0; n < 2; ++n) acc[a][b][m][n] = (f32x4){0.f, 0.f, 0.f, 0.f};
.LBB0_321:
	s_ashr_i32 s83, s82, 31
	s_lshl_b64 s[84:85], s[82:83], 19
	s_add_u32 s84, s34, s84
	s_addc_u32 s85, s35, s85
	s_and_b64 s[86:87], s[4:5], exec
	s_cselect_b32 s1, s85, s89
	s_cselect_b32 s7, s84, s88
	s_ashr_i32 s81, s80, 31
	s_lshl_b64 s[86:87], s[80:81], 19
	s_add_u32 s86, s67, s86
	s_addc_u32 s87, s69, s87
	s_and_b64 s[92:93], s[4:5], exec
	s_cselect_b32 s9, s87, s91
	s_cselect_b32 s46, s86, s90
	s_add_u32 s88, s88, 0x40080
	s_addc_u32 s89, s89, 0
	s_add_u32 s81, s90, 0x100
	v_mov_b32_e32 v2, 0
	s_addc_u32 vcc_lo, s91, 0
	s_mov_b32 vcc_hi, -2
	s_waitcnt lgkmcnt(0)
	v_mov_b32_e32 v3, v2
	v_mov_b32_e32 v4, v2
	v_mov_b32_e32 v5, v2
	v_mov_b32_e32 v6, v2
	v_mov_b32_e32 v7, v2
	v_mov_b32_e32 v8, v2
	v_mov_b32_e32 v9, v2
	v_mov_b32_e32 v18, v2
	v_mov_b32_e32 v19, v2
	v_mov_b32_e32 v20, v2
	v_mov_b32_e32 v21, v2
	v_mov_b32_e32 v22, v2
	v_mov_b32_e32 v23, v2
	v_mov_b32_e32 v24, v2
	v_mov_b32_e32 v25, v2
	v_mov_b32_e32 v34, v2
	v_mov_b32_e32 v35, v2
	v_mov_b32_e32 v36, v2
	v_mov_b32_e32 v37, v2
	v_mov_b32_e32 v38, v2
	v_mov_b32_e32 v39, v2
	v_mov_b32_e32 v40, v2
	v_mov_b32_e32 v41, v2
	v_mov_b32_e32 v50, v2
	v_mov_b32_e32 v51, v2
	v_mov_b32_e32 v52, v2
	v_mov_b32_e32 v53, v2
	v_mov_b32_e32 v54, v2
	v_mov_b32_e32 v55, v2
	v_mov_b32_e32 v56, v2
	v_mov_b32_e32 v57, v2
	v_mov_b32_e32 v10, v2
	v_mov_b32_e32 v11, v2
	v_mov_b32_e32 v12, v2
	v_mov_b32_e32 v13, v2
	v_mov_b32_e32 v14, v2
	v_mov_b32_e32 v15, v2
	v_mov_b32_e32 v16, v2
	v_mov_b32_e32 v17, v2
	v_mov_b32_e32 v26, v2
	v_mov_b32_e32 v27, v2
	v_mov_b32_e32 v28, v2
	v_mov_b32_e32 v29, v2
	v_mov_b32_e32 v30, v2
	v_mov_b32_e32 v31, v2
	v_mov_b32_e32 v32, v2
	v_mov_b32_e32 v33, v2
	v_mov_b32_e32 v42, v2
	v_mov_b32_e32 v43, v2
	v_mov_b32_e32 v44, v2
	v_mov_b32_e32 v45, v2
	v_mov_b32_e32 v46, v2
	v_mov_b32_e32 v47, v2
	v_mov_b32_e32 v48, v2
	v_mov_b32_e32 v49, v2
	v_mov_b32_e32 v58, v2
	v_mov_b32_e32 v59, v2
	v_mov_b32_e32 v60, v2
	v_mov_b32_e32 v61, v2
	v_mov_b32_e32 v62, v2
	v_mov_b32_e32 v63, v2
	v_mov_b32_e32 v64, v2
	v_mov_b32_e32 v65, v2
	v_mov_b32_e32 v66, v2
	v_mov_b32_e32 v67, v2
	v_mov_b32_e32 v68, v2
	v_mov_b32_e32 v69, v2
	v_mov_b32_e32 v70, v2
	v_mov_b32_e32 v71, v2
	v_mov_b32_e32 v72, v2
	v_mov_b32_e32 v73, v2
	v_mov_b32_e32 v82, v2
	v_mov_b32_e32 v83, v2
	v_mov_b32_e32 v84, v2
	v_mov_b32_e32 v85, v2
	v_mov_b32_e32 v86, v2
	v_mov_b32_e32 v87, v2
	v_mov_b32_e32 v88, v2
	v_mov_b32_e32 v89, v2
	v_mov_b32_e32 v98, v2
	v_mov_b32_e32 v99, v2
	v_mov_b32_e32 v100, v2
	v_mov_b32_e32 v101, v2
	v_mov_b32_e32 v102, v2
	v_mov_b32_e32 v103, v2
	v_mov_b32_e32 v104, v2
	v_mov_b32_e32 v105, v2
	v_mov_b32_e32 v114, v2
	v_mov_b32_e32 v115, v2
	v_mov_b32_e32 v116, v2
	v_mov_b32_e32 v117, v2
	v_mov_b32_e32 v118, v2
	v_mov_b32_e32 v119, v2
	v_mov_b32_e32 v120, v2
	v_mov_b32_e32 v121, v2
	v_mov_b32_e32 v74, v2
	v_mov_b32_e32 v75, v2
	v_mov_b32_e32 v76, v2
	v_mov_b32_e32 v77, v2
	v_mov_b32_e32 v78, v2
	v_mov_b32_e32 v79, v2
	v_mov_b32_e32 v80, v2
	v_mov_b32_e32 v81, v2
	v_mov_b32_e32 v90, v2
	v_mov_b32_e32 v91, v2
	v_mov_b32_e32 v92, v2
	v_mov_b32_e32 v93, v2
	v_mov_b32_e32 v94, v2
	v_mov_b32_e32 v95, v2
	v_mov_b32_e32 v96, v2
	v_mov_b32_e32 v97, v2
	v_mov_b32_e32 v106, v2
	v_mov_b32_e32 v107, v2
	v_mov_b32_e32 v108, v2
	v_mov_b32_e32 v109, v2
	v_mov_b32_e32 v110, v2
	v_mov_b32_e32 v111, v2
	v_mov_b32_e32 v112, v2
	v_mov_b32_e32 v113, v2
	v_mov_b32_e32 v122, v2
	v_mov_b32_e32 v123, v2
	v_mov_b32_e32 v124, v2
	v_mov_b32_e32 v125, v2
	v_mov_b32_e32 v126, v2
	v_mov_b32_e32 v127, v2
	v_mov_b32_e32 v128, v2
	v_mov_b32_e32 v129, v2
	s_nop 0
	s_nop 0
	s_nop 0
	s_nop 0
	s_nop 0
	s_nop 0
	s_nop 0
	s_nop 0
	s_nop 0
	s_nop 0
	s_nop 0
	s_nop 0
	s_nop 0

; #define AT_STAGE(gbase, so, i, ldsoff) do { const int _ii = (i) < NT ? (i) : NT - 1; const size_t _go = (size_t)((tstart + _ii) & tmask) * (64 * 1024); _Pragma("unroll") for (int _i = 0; _i < 2; ++_i) \
;         __builtin_amdgcn_global_load_lds((const unsigned*)((gbase) + _go + (so)[_i]), (LAS unsigned*)(lds + (ldsoff) + (2 * w + _i) * 1024), 16, 0, 0); } while (0)
; #define AT_BAR(N) asm volatile("s_waitcnt vmcnt(" #N ") lgkmcnt(0)\n\ts_barrier" ::: "memory")
; __device__ __forceinline__ void attn_unit(LAS unsigned char* lds, int seq, int h, int qb, bf16_t* UQ, const bf16_t* KB, const bf16_t* VB, const float* rel_bias, const float* subln, float lam, float bmax) {
;     ...
;     for (int i = 1; i < NT - 1; ++i) {
;         AT_STAGE(kg, kso, i + 3, k_i); AT_STAGE(vg, vso, i + 2, AT_V0 + ((i + 2) & 3) * AT_TILE);
;         AT_TB((tstart + i + 1) & tmask);
;         attn_step<true, true>(lds + k_n, lds0 + AT_V0 + ((i - 1) & 3) * AT_TILE, kfo, vo, qf, s, pf, o, ol, tbv);
;         AT_BAR(4);
;         { const int tmp = k_i; k_i = k_n; k_n = k_p; k_p = tmp; }
;     }
.Lat_xskip_s:
	s_nop 0
	s_nop 0
	s_nop 0
	s_nop 0
	s_nop 0
	s_nop 0
	s_nop 0
	s_nop 0
	s_nop 0
	s_nop 0
	s_nop 0
	s_nop 0
	s_nop 0

; #define AT_STAGE(gbase, so, i, ldsoff) do { const int _ii = (i) < NT ? (i) : NT - 1; const size_t _go = (size_t)((tstart + _ii) & tmask) * (64 * 1024); _Pragma("unroll") for (int _i = 0; _i < 2; ++_i) \
;         __builtin_amdgcn_global_load_lds((const unsigned*)((gbase) + _go + (so)[_i]), (LAS unsigned*)(lds + (ldsoff) + (2 * w + _i) * 1024), 16, 0, 0); } while (0)
; #define AT_BAR(N) asm volatile("s_waitcnt vmcnt(" #N ") lgkmcnt(0)\n\ts_barrier" ::: "memory")
; __device__ __forceinline__ void attn_unit(LAS unsigned char* lds, int seq, int h, int qb, bf16_t* UQ, const bf16_t* KB, const bf16_t* VB, const float* rel_bias, const float* subln, float lam, float bmax) {
;     ...
;     for (int i = 1; i < NT - 1; ++i) {
;         AT_STAGE(kg, kso, i + 3, k_i); AT_STAGE(vg, vso, i + 2, AT_V0 + ((i + 2) & 3) * AT_TILE);
;         AT_TB((tstart + i + 1) & tmask);
;         attn_step<true, true>(lds + k_n, lds0 + AT_V0 + ((i - 1) & 3) * AT_TILE, kfo, vo, qf, s, pf, o, ol, tbv);
;         AT_BAR(4);
;         { const int tmp = k_i; k_i = k_n; k_n = k_p; k_p = tmp; }
;     }
.Lat_xskip_p:
	s_nop 0
	s_nop 0

; template <class Epi>
; __device__ __forceinline__ void gemm_phase(LAS unsigned char* lds, const Gemm g, const StaticOrder& S, const Epi& E) {
;     ...
;     for (;;) {
;         const bool has_next = S.next(ui + 1, nxt);
;         const char* nA = has_next ? (const char*)g.A + (size_t)nxt.pm * tstep : cA; const char* nB = has_next ? (const char*)g.Bt + (size_t)nxt.pn * tstep : cB;
;     ...
; #pragma unroll
;         for (int a = 0; a < 2; ++a)
; #pragma unroll
;             for (int b = 0; b < 2; ++b)
; #pragma unroll
;                 for (int m = 0; m < 4; ++m)
; #pragma unroll
;                     for (int n = 0; n < 2; ++n) acc[a][b][m][n] = (f32x4){0.f, 0.f, 0.f, 0.f};
.LBB0_618:
	s_ashr_i32 s27, s26, 31
	s_lshl_b64 s[38:39], s[26:27], 19
	s_add_u32 s38, s34, s38
	s_addc_u32 s39, s35, s39
	s_and_b64 s[40:41], s[2:3], exec
	s_cselect_b32 s64, s39, s45
	s_cselect_b32 s65, s38, s44
	s_ashr_i32 s25, s24, 31
	s_lshl_b64 s[40:41], s[24:25], 19
	s_add_u32 s40, s33, s40
	s_addc_u32 s41, s50, s41
	s_and_b64 s[48:49], s[2:3], exec
	s_cselect_b32 s25, s41, s47
	s_cselect_b32 s66, s40, s46
	s_add_u32 s44, s44, 0x40080
	s_addc_u32 s45, s45, 0
	s_add_u32 s67, s46, 0x100
	v_mov_b32_e32 v2, 0
	s_addc_u32 s68, s47, 0
	s_mov_b32 s69, -2
	v_mov_b32_e32 v3, v2
	v_mov_b32_e32 v4, v2
	v_mov_b32_e32 v5, v2
	v_mov_b32_e32 v6, v2
	v_mov_b32_e32 v7, v2
	v_mov_b32_e32 v8, v2
	v_mov_b32_e32 v9, v2
	v_mov_b32_e32 v18, v2
	v_mov_b32_e32 v19, v2
	v_mov_b32_e32 v20, v2
	v_mov_b32_e32 v21, v2
	v_mov_b32_e32 v22, v2
	v_mov_b32_e32 v23, v2
	v_mov_b32_e32 v24, v2
	v_mov_b32_e32 v25, v2
	v_mov_b32_e32 v34, v2
	v_mov_b32_e32 v35, v2
	v_mov_b32_e32 v36, v2
	v_mov_b32_e32 v37, v2
	v_mov_b32_e32 v38, v2
	v_mov_b32_e32 v39, v2
	v_mov_b32_e32 v40, v2
	v_mov_b32_e32 v41, v2
	v_mov_b32_e32 v50, v2
	v_mov_b32_e32 v51, v2
	v_mov_b32_e32 v52, v2
	v_mov_b32_e32 v53, v2
	v_mov_b32_e32 v54, v2
	v_mov_b32_e32 v55, v2
	v_mov_b32_e32 v56, v2
	v_mov_b32_e32 v57, v2
	v_mov_b32_e32 v10, v2
	v_mov_b32_e32 v11, v2
	v_mov_b32_e32 v12, v2
	v_mov_b32_e32 v13, v2
	v_mov_b32_e32 v14, v2
	v_mov_b32_e32 v15, v2
	v_mov_b32_e32 v16, v2
	v_mov_b32_e32 v17, v2
	v_mov_b32_e32 v26, v2
	v_mov_b32_e32 v27, v2
	v_mov_b32_e32 v28, v2
	v_mov_b32_e32 v29, v2
	v_mov_b32_e32 v30, v2
	v_mov_b32_e32 v31, v2
	v_mov_b32_e32 v32, v2
	v_mov_b32_e32 v33, v2
	v_mov_b32_e32 v42, v2
	v_mov_b32_e32 v43, v2
	v_mov_b32_e32 v44, v2
	v_mov_b32_e32 v45, v2
	v_mov_b32_e32 v46, v2
	v_mov_b32_e32 v47, v2
	v_mov_b32_e32 v48, v2
	v_mov_b32_e32 v49, v2
	v_mov_b32_e32 v58, v2
	v_mov_b32_e32 v59, v2
	v_mov_b32_e32 v60, v2
	v_mov_b32_e32 v61, v2
	v_mov_b32_e32 v62, v2
	v_mov_b32_e32 v63, v2
	v_mov_b32_e32 v64, v2
	v_mov_b32_e32 v65, v2
	v_mov_b32_e32 v66, v2
	v_mov_b32_e32 v67, v2
	v_mov_b32_e32 v68, v2
	v_mov_b32_e32 v69, v2
	v_mov_b32_e32 v70, v2
	v_mov_b32_e32 v71, v2
	v_mov_b32_e32 v72, v2
	v_mov_b32_e32 v73, v2
	v_mov_b32_e32 v82, v2
	v_mov_b32_e32 v83, v2
	v_mov_b32_e32 v84, v2
	v_mov_b32_e32 v85, v2
	v_mov_b32_e32 v86, v2
	v_mov_b32_e32 v87, v2
	v_mov_b32_e32 v88, v2
	v_mov_b32_e32 v89, v2
	v_mov_b32_e32 v98, v2
	v_mov_b32_e32 v99, v2
	v_mov_b32_e32 v100, v2
	v_mov_b32_e32 v101, v2
	v_mov_b32_e32 v102, v2
	v_mov_b32_e32 v103, v2
	v_mov_b32_e32 v104, v2
	v_mov_b32_e32 v105, v2
	v_mov_b32_e32 v114, v2
	v_mov_b32_e32 v115, v2
	v_mov_b32_e32 v116, v2
	v_mov_b32_e32 v117, v2
	v_mov_b32_e32 v118, v2
	v_mov_b32_e32 v119, v2
	v_mov_b32_e32 v120, v2
	v_mov_b32_e32 v121, v2
	v_mov_b32_e32 v74, v2
	v_mov_b32_e32 v75, v2
	v_mov_b32_e32 v76, v2
	v_mov_b32_e32 v77, v2
	v_mov_b32_e32 v78, v2
	v_mov_b32_e32 v79, v2
	v_mov_b32_e32 v80, v2
	v_mov_b32_e32 v81, v2
	v_mov_b32_e32 v90, v2
	v_mov_b32_e32 v91, v2
	v_mov_b32_e32 v92, v2
	v_mov_b32_e32 v93, v2
	v_mov_b32_e32 v94, v2
	v_mov_b32_e32 v95, v2
	v_mov_b32_e32 v96, v2
	v_mov_b32_e32 v97, v2
	v_mov_b32_e32 v106, v2
	v_mov_b32_e32 v107, v2
	v_mov_b32_e32 v108, v2
	v_mov_b32_e32 v109, v2
	v_mov_b32_e32 v110, v2
	v_mov_b32_e32 v111, v2
	v_mov_b32_e32 v112, v2
	v_mov_b32_e32 v113, v2
	v_mov_b32_e32 v122, v2
	v_mov_b32_e32 v123, v2
	v_mov_b32_e32 v124, v2
	v_mov_b32_e32 v125, v2
	v_mov_b32_e32 v126, v2
	v_mov_b32_e32 v127, v2
	v_mov_b32_e32 v128, v2
	v_mov_b32_e32 v129, v2
	s_nop 0
	s_nop 0
	s_nop 0

; template <class Epi>
; __device__ __forceinline__ void gemm_phase(LAS unsigned char* lds, const Gemm g, const StaticOrder& S, const Epi& E) {
;     ...
;     for (;;) {
;         const bool has_next = S.next(ui + 1, nxt);
;         const char* nA = has_next ? (const char*)g.A + (size_t)nxt.pm * tstep : cA; const char* nB = has_next ? (const char*)g.Bt + (size_t)nxt.pn * tstep : cB;
;     ...
; #pragma unroll
;         for (int a = 0; a < 2; ++a)
; #pragma unroll
;             for (int b = 0; b < 2; ++b)
; #pragma unroll
;                 for (int m = 0; m < 4; ++m)
; #pragma unroll
;                     for (int n = 0; n < 2; ++n) acc[a][b][m][n] = (f32x4){0.f, 0.f, 0.f, 0.f};
.LBB0_699:
	s_ashr_i32 s43, s42, 31
	s_lshl_b64 s[44:45], s[42:43], 19
	s_add_u32 s44, s36, s44
	s_addc_u32 s45, s37, s45
	s_and_b64 s[46:47], s[0:1], exec
	s_cselect_b32 s43, s45, s49
	s_cselect_b32 s76, s44, s48
	s_ashr_i32 s41, s40, 31
	s_lshl_b64 s[46:47], s[40:41], 19
	s_add_u32 s46, s11, s46
	s_addc_u32 s47, s33, s47
	s_and_b64 s[54:55], s[0:1], exec
	v_mov_b32_e32 v4, v2
	v_mov_b32_e32 v5, v2
	s_cselect_b32 s41, s47, s53
	s_cselect_b32 s77, s46, s52
	s_add_u32 s78, s52, 0x100
	v_mov_b32_e32 v3, v2
	v_mov_b64_e32 v[8:9], v[4:5]
	v_mov_b64_e32 v[12:13], v[4:5]
	v_mov_b64_e32 v[24:25], v[4:5]
	v_mov_b64_e32 v[28:29], v[4:5]
	v_mov_b64_e32 v[40:41], v[4:5]
	v_mov_b64_e32 v[44:45], v[4:5]
	v_mov_b64_e32 v[56:57], v[4:5]
	v_mov_b64_e32 v[60:61], v[4:5]
	v_mov_b64_e32 v[16:17], v[4:5]
	v_mov_b64_e32 v[20:21], v[4:5]
	v_mov_b64_e32 v[32:33], v[4:5]
	v_mov_b64_e32 v[36:37], v[4:5]
	v_mov_b64_e32 v[48:49], v[4:5]
	v_mov_b64_e32 v[52:53], v[4:5]
	v_mov_b64_e32 v[64:65], v[4:5]
	v_mov_b64_e32 v[68:69], v[4:5]
	v_mov_b64_e32 v[72:73], v[4:5]
	v_mov_b64_e32 v[76:77], v[4:5]
	v_mov_b64_e32 v[88:89], v[4:5]
	v_mov_b64_e32 v[92:93], v[4:5]
	v_mov_b64_e32 v[104:105], v[4:5]
	v_mov_b64_e32 v[108:109], v[4:5]
	v_mov_b64_e32 v[120:121], v[4:5]
	v_mov_b64_e32 v[124:125], v[4:5]
	v_mov_b64_e32 v[80:81], v[4:5]
	v_mov_b64_e32 v[84:85], v[4:5]
	v_mov_b64_e32 v[96:97], v[4:5]
	v_mov_b64_e32 v[100:101], v[4:5]
	v_mov_b64_e32 v[112:113], v[4:5]
	v_mov_b64_e32 v[116:117], v[4:5]
	v_mov_b64_e32 v[128:129], v[4:5]
	v_mov_b64_e32 v[132:133], v[4:5]
	v_lshl_or_b32 v152, s51, 8, v199
	v_lshl_add_u32 v150, s50, 8, v1
	v_lshl_add_u64 v[154:155], s[48:49], 0, v[180:181]
	v_lshl_add_u64 v[156:157], s[48:49], 0, v[182:183]
	s_addc_u32 s79, s53, 0
	s_mov_b32 s80, -2
	s_mov_b64 s[50:51], 0
	v_mov_b64_e32 v[6:7], v[2:3]
	v_mov_b64_e32 v[10:11], v[2:3]
	v_mov_b64_e32 v[22:23], v[2:3]
	v_mov_b64_e32 v[26:27], v[2:3]
	v_mov_b64_e32 v[38:39], v[2:3]
	v_mov_b64_e32 v[42:43], v[2:3]
	v_mov_b64_e32 v[54:55], v[2:3]
	v_mov_b64_e32 v[58:59], v[2:3]
	v_mov_b64_e32 v[14:15], v[2:3]
	v_mov_b64_e32 v[18:19], v[2:3]
	v_mov_b64_e32 v[30:31], v[2:3]
	v_mov_b64_e32 v[34:35], v[2:3]
	v_mov_b64_e32 v[46:47], v[2:3]
	v_mov_b64_e32 v[50:51], v[2:3]
	v_mov_b64_e32 v[62:63], v[2:3]
	v_mov_b64_e32 v[66:67], v[2:3]
	v_mov_b64_e32 v[70:71], v[2:3]
	v_mov_b64_e32 v[74:75], v[2:3]
	v_mov_b64_e32 v[86:87], v[2:3]
	v_mov_b64_e32 v[90:91], v[2:3]
	v_mov_b64_e32 v[102:103], v[2:3]
	v_mov_b64_e32 v[106:107], v[2:3]
	v_mov_b64_e32 v[118:119], v[2:3]
	v_mov_b64_e32 v[122:123], v[2:3]
	v_mov_b64_e32 v[78:79], v[2:3]
	v_mov_b64_e32 v[82:83], v[2:3]
	v_mov_b64_e32 v[94:95], v[2:3]
	v_mov_b64_e32 v[98:99], v[2:3]
	v_mov_b64_e32 v[110:111], v[2:3]
	v_mov_b64_e32 v[114:115], v[2:3]
	v_mov_b64_e32 v[126:127], v[2:3]
	v_mov_b64_e32 v[130:131], v[2:3]
	s_branch .LBB0_701
	s_nop 0

; template <class Epi>
; __device__ __forceinline__ void gemm_phase(LAS unsigned char* lds, const Gemm g, const StaticOrder& S, const Epi& E) {
;     ...
;     for (;;) {
;         const bool has_next = S.next(ui + 1, nxt);
;         const char* nA = has_next ? (const char*)g.A + (size_t)nxt.pm * tstep : cA; const char* nB = has_next ? (const char*)g.Bt + (size_t)nxt.pn * tstep : cB;
;     ...
; #pragma unroll
;         for (int a = 0; a < 2; ++a)
; #pragma unroll
;             for (int b = 0; b < 2; ++b)
; #pragma unroll
;                 for (int m = 0; m < 4; ++m)
; #pragma unroll
;                     for (int n = 0; n < 2; ++n) acc[a][b][m][n] = (f32x4){0.f, 0.f, 0.f, 0.f};
.LBB0_784:
	s_ashr_i32 s21, s20, 31
	s_lshl_b64 s[22:23], s[20:21], 19
	s_add_u32 s22, s16, s22
	s_addc_u32 s23, s17, s23
	s_and_b64 s[24:25], s[2:3], exec
	s_cselect_b32 s21, s23, s39
	s_cselect_b32 s27, s22, s38
	s_ashr_i32 s19, s18, 31
	s_lshl_b64 s[24:25], s[18:19], 19
	s_add_u32 s24, s11, s24
	s_addc_u32 s25, s33, s25
	s_and_b64 s[42:43], s[2:3], exec
	s_cselect_b32 s19, s25, s41
	s_cselect_b32 s60, s24, s40
	s_add_u32 s38, s38, 0x40080
	s_addc_u32 s39, s39, 0
	s_add_u32 s61, s40, 0x100
	v_mov_b32_e32 v2, 0
	s_addc_u32 s62, s41, 0
	s_mov_b32 s63, -2
	s_waitcnt lgkmcnt(0)
	v_mov_b32_e32 v3, v2
	v_mov_b32_e32 v4, v2
	v_mov_b32_e32 v5, v2
	v_mov_b32_e32 v6, v2
	v_mov_b32_e32 v7, v2
	v_mov_b32_e32 v8, v2
	v_mov_b32_e32 v9, v2
	v_mov_b32_e32 v18, v2
	v_mov_b32_e32 v19, v2
	v_mov_b32_e32 v20, v2
	v_mov_b32_e32 v21, v2
	v_mov_b32_e32 v22, v2
	v_mov_b32_e32 v23, v2
	v_mov_b32_e32 v24, v2
	v_mov_b32_e32 v25, v2
	v_mov_b32_e32 v34, v2
	v_mov_b32_e32 v35, v2
	v_mov_b32_e32 v36, v2
	v_mov_b32_e32 v37, v2
	v_mov_b32_e32 v38, v2
	v_mov_b32_e32 v39, v2
	v_mov_b32_e32 v40, v2
	v_mov_b32_e32 v41, v2
	v_mov_b32_e32 v50, v2
	v_mov_b32_e32 v51, v2
	v_mov_b32_e32 v52, v2
	v_mov_b32_e32 v53, v2
	v_mov_b32_e32 v54, v2
	v_mov_b32_e32 v55, v2
	v_mov_b32_e32 v56, v2
	v_mov_b32_e32 v57, v2
	v_mov_b32_e32 v10, v2
	v_mov_b32_e32 v11, v2
	v_mov_b32_e32 v12, v2
	v_mov_b32_e32 v13, v2
	v_mov_b32_e32 v14, v2
	v_mov_b32_e32 v15, v2
	v_mov_b32_e32 v16, v2
	v_mov_b32_e32 v17, v2
	v_mov_b32_e32 v26, v2
	v_mov_b32_e32 v27, v2
	v_mov_b32_e32 v28, v2
	v_mov_b32_e32 v29, v2
	v_mov_b32_e32 v30, v2
	v_mov_b32_e32 v31, v2
	v_mov_b32_e32 v32, v2
	v_mov_b32_e32 v33, v2
	v_mov_b32_e32 v42, v2
	v_mov_b32_e32 v43, v2
	v_mov_b32_e32 v44, v2
	v_mov_b32_e32 v45, v2
	v_mov_b32_e32 v46, v2
	v_mov_b32_e32 v47, v2
	v_mov_b32_e32 v48, v2
	v_mov_b32_e32 v49, v2
	v_mov_b32_e32 v58, v2
	v_mov_b32_e32 v59, v2
	v_mov_b32_e32 v60, v2
	v_mov_b32_e32 v61, v2
	v_mov_b32_e32 v62, v2
	v_mov_b32_e32 v63, v2
	v_mov_b32_e32 v64, v2
	v_mov_b32_e32 v65, v2
	v_mov_b32_e32 v66, v2
	v_mov_b32_e32 v67, v2
	v_mov_b32_e32 v68, v2
	v_mov_b32_e32 v69, v2
	v_mov_b32_e32 v70, v2
	v_mov_b32_e32 v71, v2
	v_mov_b32_e32 v72, v2
	v_mov_b32_e32 v73, v2
	v_mov_b32_e32 v82, v2
	v_mov_b32_e32 v83, v2
	v_mov_b32_e32 v84, v2
	v_mov_b32_e32 v85, v2
	v_mov_b32_e32 v86, v2
	v_mov_b32_e32 v87, v2
	v_mov_b32_e32 v88, v2
	v_mov_b32_e32 v89, v2
	v_mov_b32_e32 v98, v2
	v_mov_b32_e32 v99, v2
	v_mov_b32_e32 v100, v2
	v_mov_b32_e32 v101, v2
	v_mov_b32_e32 v102, v2
	v_mov_b32_e32 v103, v2
	v_mov_b32_e32 v104, v2
	v_mov_b32_e32 v105, v2
	v_mov_b32_e32 v114, v2
	v_mov_b32_e32 v115, v2
	v_mov_b32_e32 v116, v2
	v_mov_b32_e32 v117, v2
	v_mov_b32_e32 v118, v2
	v_mov_b32_e32 v119, v2
	v_mov_b32_e32 v120, v2
	v_mov_b32_e32 v121, v2
	v_mov_b32_e32 v74, v2
	v_mov_b32_e32 v75, v2
	v_mov_b32_e32 v76, v2
	v_mov_b32_e32 v77, v2
	v_mov_b32_e32 v78, v2
	v_mov_b32_e32 v79, v2
	v_mov_b32_e32 v80, v2
	v_mov_b32_e32 v81, v2
	v_mov_b32_e32 v90, v2
	v_mov_b32_e32 v91, v2
	v_mov_b32_e32 v92, v2
	v_mov_b32_e32 v93, v2
	v_mov_b32_e32 v94, v2
	v_mov_b32_e32 v95, v2
	v_mov_b32_e32 v96, v2
	v_mov_b32_e32 v97, v2
	v_mov_b32_e32 v106, v2
	v_mov_b32_e32 v107, v2
	v_mov_b32_e32 v108, v2
	v_mov_b32_e32 v109, v2
	v_mov_b32_e32 v110, v2
	v_mov_b32_e32 v111, v2
	v_mov_b32_e32 v112, v2
	v_mov_b32_e32 v113, v2
	v_mov_b32_e32 v122, v2
	v_mov_b32_e32 v123, v2
	v_mov_b32_e32 v124, v2
	v_mov_b32_e32 v125, v2
	v_mov_b32_e32 v126, v2
	v_mov_b32_e32 v127, v2
	v_mov_b32_e32 v128, v2
	v_mov_b32_e32 v129, v2
	s_nop 0
	s_nop 0
	s_nop 0
	s_nop 0
	s_nop 0
	s_nop 0
	s_nop 0
	s_nop 0
	s_nop 0
	s_nop 0
	s_nop 0

; template <class Epi>
; __device__ __forceinline__ void gemm_phase(LAS unsigned char* lds, const Gemm g, const StaticOrder& S, const Epi& E) {
;     ...
;     for (;;) {
;         const bool has_next = S.next(ui + 1, nxt);
;         const char* nA = has_next ? (const char*)g.A + (size_t)nxt.pm * tstep : cA; const char* nB = has_next ? (const char*)g.Bt + (size_t)nxt.pn * tstep : cB;
;     ...
; #pragma unroll
;         for (int a = 0; a < 2; ++a)
; #pragma unroll
;             for (int b = 0; b < 2; ++b)
; #pragma unroll
;                 for (int m = 0; m < 4; ++m)
; #pragma unroll
;                     for (int n = 0; n < 2; ++n) acc[a][b][m][n] = (f32x4){0.f, 0.f, 0.f, 0.f};
.LBB0_883:
	s_ashr_i32 s25, s24, 31
	s_lshl_b64 s[26:27], s[24:25], 19
	s_add_u32 s26, s36, s26
	s_addc_u32 s27, s37, s27
	s_and_b64 s[38:39], s[2:3], exec
	s_cselect_b32 s62, s27, s45
	s_cselect_b32 s63, s26, s44
	s_ashr_i32 s23, s22, 31
	s_lshl_b64 s[38:39], s[22:23], 19
	s_add_u32 s38, s33, s38
	s_addc_u32 s39, s50, s39
	s_and_b64 s[48:49], s[2:3], exec
	s_cselect_b32 s23, s39, s47
	s_cselect_b32 s64, s38, s46
	s_add_u32 s44, s44, 0x40080
	s_addc_u32 s45, s45, 0
	s_add_u32 s65, s46, 0x100
	v_mov_b32_e32 v2, 0
	s_addc_u32 s66, s47, 0
	s_mov_b32 s67, -2
	v_mov_b32_e32 v3, v2
	v_mov_b32_e32 v4, v2
	v_mov_b32_e32 v5, v2
	v_mov_b32_e32 v10, v2
	v_mov_b32_e32 v11, v2
	v_mov_b32_e32 v12, v2
	v_mov_b32_e32 v13, v2
	v_mov_b32_e32 v18, v2
	v_mov_b32_e32 v19, v2
	v_mov_b32_e32 v20, v2
	v_mov_b32_e32 v21, v2
	v_mov_b32_e32 v26, v2
	v_mov_b32_e32 v27, v2
	v_mov_b32_e32 v28, v2
	v_mov_b32_e32 v29, v2
	v_mov_b32_e32 v34, v2
	v_mov_b32_e32 v35, v2
	v_mov_b32_e32 v36, v2
	v_mov_b32_e32 v37, v2
	v_mov_b32_e32 v42, v2
	v_mov_b32_e32 v43, v2
	v_mov_b32_e32 v44, v2
	v_mov_b32_e32 v45, v2
	v_mov_b32_e32 v50, v2
	v_mov_b32_e32 v51, v2
	v_mov_b32_e32 v52, v2
	v_mov_b32_e32 v53, v2
	v_mov_b32_e32 v58, v2
	v_mov_b32_e32 v59, v2
	v_mov_b32_e32 v60, v2
	v_mov_b32_e32 v61, v2
	v_mov_b32_e32 v6, v2
	v_mov_b32_e32 v7, v2
	v_mov_b32_e32 v8, v2
	v_mov_b32_e32 v9, v2
	v_mov_b32_e32 v14, v2
	v_mov_b32_e32 v15, v2
	v_mov_b32_e32 v16, v2
	v_mov_b32_e32 v17, v2
	v_mov_b32_e32 v22, v2
	v_mov_b32_e32 v23, v2
	v_mov_b32_e32 v24, v2
	v_mov_b32_e32 v25, v2
	v_mov_b32_e32 v30, v2
	v_mov_b32_e32 v31, v2
	v_mov_b32_e32 v32, v2
	v_mov_b32_e32 v33, v2
	v_mov_b32_e32 v38, v2
	v_mov_b32_e32 v39, v2
	v_mov_b32_e32 v40, v2
	v_mov_b32_e32 v41, v2
	v_mov_b32_e32 v46, v2
	v_mov_b32_e32 v47, v2
	v_mov_b32_e32 v48, v2
	v_mov_b32_e32 v49, v2
	v_mov_b32_e32 v54, v2
	v_mov_b32_e32 v55, v2
	v_mov_b32_e32 v56, v2
	v_mov_b32_e32 v57, v2
	v_mov_b32_e32 v62, v2
	v_mov_b32_e32 v63, v2
	v_mov_b32_e32 v64, v2
	v_mov_b32_e32 v65, v2
	v_mov_b32_e32 v66, v2
	v_mov_b32_e32 v67, v2
	v_mov_b32_e32 v68, v2
	v_mov_b32_e32 v69, v2
	v_mov_b32_e32 v74, v2
	v_mov_b32_e32 v75, v2
	v_mov_b32_e32 v76, v2
	v_mov_b32_e32 v77, v2
	v_mov_b32_e32 v82, v2
	v_mov_b32_e32 v83, v2
	v_mov_b32_e32 v84, v2
	v_mov_b32_e32 v85, v2
	v_mov_b32_e32 v90, v2
	v_mov_b32_e32 v91, v2
	v_mov_b32_e32 v92, v2
	v_mov_b32_e32 v93, v2
	v_mov_b32_e32 v98, v2
	v_mov_b32_e32 v99, v2
	v_mov_b32_e32 v100, v2
	v_mov_b32_e32 v101, v2
	v_mov_b32_e32 v106, v2
	v_mov_b32_e32 v107, v2
	v_mov_b32_e32 v108, v2
	v_mov_b32_e32 v109, v2
	v_mov_b32_e32 v114, v2
	v_mov_b32_e32 v115, v2
	v_mov_b32_e32 v116, v2
	v_mov_b32_e32 v117, v2
	v_mov_b32_e32 v122, v2
	v_mov_b32_e32 v123, v2
	v_mov_b32_e32 v124, v2
	v_mov_b32_e32 v125, v2
	v_mov_b32_e32 v70, v2
	v_mov_b32_e32 v71, v2
	v_mov_b32_e32 v72, v2
	v_mov_b32_e32 v73, v2
	v_mov_b32_e32 v78, v2
	v_mov_b32_e32 v79, v2
	v_mov_b32_e32 v80, v2
	v_mov_b32_e32 v81, v2
	v_mov_b32_e32 v86, v2
	v_mov_b32_e32 v87, v2
	v_mov_b32_e32 v88, v2
	v_mov_b32_e32 v89, v2
	v_mov_b32_e32 v94, v2
	v_mov_b32_e32 v95, v2
	v_mov_b32_e32 v96, v2
	v_mov_b32_e32 v97, v2
	v_mov_b32_e32 v102, v2
	v_mov_b32_e32 v103, v2
	v_mov_b32_e32 v104, v2
	v_mov_b32_e32 v105, v2
	v_mov_b32_e32 v110, v2
	v_mov_b32_e32 v111, v2
	v_mov_b32_e32 v112, v2
	v_mov_b32_e32 v113, v2
	v_mov_b32_e32 v118, v2
	v_mov_b32_e32 v119, v2
	v_mov_b32_e32 v120, v2
	v_mov_b32_e32 v121, v2
	v_mov_b32_e32 v126, v2
	v_mov_b32_e32 v127, v2
	v_mov_b32_e32 v128, v2
	v_mov_b32_e32 v129, v2
	s_nop 0
	s_nop 0
	s_nop 0
	s_nop 0
	s_nop 0
	s_nop 0
	s_nop 0
	s_nop 0
	s_nop 0
	s_nop 0
	s_nop 0
	s_nop 0
	s_nop 0

; template <class Epi>
; __device__ __forceinline__ void gemm_phase(LAS unsigned char* lds, const Gemm g, const StaticOrder& S, const Epi& E) {
;     ...
;     for (;;) {
;         const bool has_next = S.next(ui + 1, nxt);
;         const char* nA = has_next ? (const char*)g.A + (size_t)nxt.pm * tstep : cA; const char* nB = has_next ? (const char*)g.Bt + (size_t)nxt.pn * tstep : cB;
;         for (int t = 0; t < nt; t += 2) {
;             const bool last = (t == nt - 2);
;             const char* a1 = cA + (size_t)(t + 1) * kstep;
;             const char* a2 = last ? nA : cA + (size_t)(t + 2) * kstep; const char* b2 = last ? nB : cB + (size_t)(t + 2) * kstep;
;     ...
; #pragma unroll
;         for (int a = 0; a < 2; ++a)
; #pragma unroll
;             for (int b = 0; b < 2; ++b)
; #pragma unroll
;                 for (int m = 0; m < 4; ++m)
; #pragma unroll
;                     for (int n = 0; n < 2; ++n) acc[a][b][m][n] = (f32x4){0.f, 0.f, 0.f, 0.f};
.LBB0_970:
	s_add_u32 s22, s22, 0xb0080
	s_addc_u32 s23, s23, 0
	s_add_u32 s57, s24, 0x100
	v_mov_b32_e32 v2, 0
	s_addc_u32 s58, s25, 0
	s_mov_b32 s59, -2
	s_waitcnt lgkmcnt(0)
	v_mov_b32_e32 v3, v2
	v_mov_b32_e32 v4, v2
	v_mov_b32_e32 v5, v2
	v_mov_b32_e32 v6, v2
	v_mov_b32_e32 v7, v2
	v_mov_b32_e32 v8, v2
	v_mov_b32_e32 v9, v2
	v_mov_b32_e32 v18, v2
	v_mov_b32_e32 v19, v2
	v_mov_b32_e32 v20, v2
	v_mov_b32_e32 v21, v2
	v_mov_b32_e32 v22, v2
	v_mov_b32_e32 v23, v2
	v_mov_b32_e32 v24, v2
	v_mov_b32_e32 v25, v2
	v_mov_b32_e32 v34, v2
	v_mov_b32_e32 v35, v2
	v_mov_b32_e32 v36, v2
	v_mov_b32_e32 v37, v2
	v_mov_b32_e32 v38, v2
	v_mov_b32_e32 v39, v2
	v_mov_b32_e32 v40, v2
	v_mov_b32_e32 v41, v2
	v_mov_b32_e32 v50, v2
	v_mov_b32_e32 v51, v2
	v_mov_b32_e32 v52, v2
	v_mov_b32_e32 v53, v2
	v_mov_b32_e32 v54, v2
	v_mov_b32_e32 v55, v2
	v_mov_b32_e32 v56, v2
	v_mov_b32_e32 v57, v2
	v_mov_b32_e32 v10, v2
	v_mov_b32_e32 v11, v2
	v_mov_b32_e32 v12, v2
	v_mov_b32_e32 v13, v2
	v_mov_b32_e32 v14, v2
	v_mov_b32_e32 v15, v2
	v_mov_b32_e32 v16, v2
	v_mov_b32_e32 v17, v2
	v_mov_b32_e32 v26, v2
	v_mov_b32_e32 v27, v2
	v_mov_b32_e32 v28, v2
	v_mov_b32_e32 v29, v2
	v_mov_b32_e32 v30, v2
	v_mov_b32_e32 v31, v2
	v_mov_b32_e32 v32, v2
	v_mov_b32_e32 v33, v2
	v_mov_b32_e32 v42, v2
	v_mov_b32_e32 v43, v2
	v_mov_b32_e32 v44, v2
	v_mov_b32_e32 v45, v2
	v_mov_b32_e32 v46, v2
	v_mov_b32_e32 v47, v2
	v_mov_b32_e32 v48, v2
	v_mov_b32_e32 v49, v2
	v_mov_b32_e32 v58, v2
	v_mov_b32_e32 v59, v2
	v_mov_b32_e32 v60, v2
	v_mov_b32_e32 v61, v2
	v_mov_b32_e32 v62, v2
	v_mov_b32_e32 v63, v2
	v_mov_b32_e32 v64, v2
	v_mov_b32_e32 v65, v2
	v_mov_b32_e32 v66, v2
	v_mov_b32_e32 v67, v2
	v_mov_b32_e32 v68, v2
	v_mov_b32_e32 v69, v2
	v_mov_b32_e32 v70, v2
	v_mov_b32_e32 v71, v2
	v_mov_b32_e32 v72, v2
	v_mov_b32_e32 v73, v2
	v_mov_b32_e32 v82, v2
	v_mov_b32_e32 v83, v2
	v_mov_b32_e32 v84, v2
	v_mov_b32_e32 v85, v2
	v_mov_b32_e32 v86, v2
	v_mov_b32_e32 v87, v2
	v_mov_b32_e32 v88, v2
	v_mov_b32_e32 v89, v2
	v_mov_b32_e32 v98, v2
	v_mov_b32_e32 v99, v2
	v_mov_b32_e32 v100, v2
	v_mov_b32_e32 v101, v2
	v_mov_b32_e32 v102, v2
	v_mov_b32_e32 v103, v2
	v_mov_b32_e32 v104, v2
	v_mov_b32_e32 v105, v2
	v_mov_b32_e32 v114, v2
	v_mov_b32_e32 v115, v2
	v_mov_b32_e32 v116, v2
	v_mov_b32_e32 v117, v2
	v_mov_b32_e32 v118, v2
	v_mov_b32_e32 v119, v2
	v_mov_b32_e32 v120, v2
	v_mov_b32_e32 v121, v2
	v_mov_b32_e32 v74, v2
	v_mov_b32_e32 v75, v2
	v_mov_b32_e32 v76, v2
	v_mov_b32_e32 v77, v2
	v_mov_b32_e32 v78, v2
	v_mov_b32_e32 v79, v2
	v_mov_b32_e32 v80, v2
	v_mov_b32_e32 v81, v2
	v_mov_b32_e32 v90, v2
	v_mov_b32_e32 v91, v2
	v_mov_b32_e32 v92, v2
	v_mov_b32_e32 v93, v2
	v_mov_b32_e32 v94, v2
	v_mov_b32_e32 v95, v2
	v_mov_b32_e32 v96, v2
	v_mov_b32_e32 v97, v2
	v_mov_b32_e32 v106, v2
	v_mov_b32_e32 v107, v2
	v_mov_b32_e32 v108, v2
	v_mov_b32_e32 v109, v2
	v_mov_b32_e32 v110, v2
	v_mov_b32_e32 v111, v2
	v_mov_b32_e32 v112, v2
	v_mov_b32_e32 v113, v2
	v_mov_b32_e32 v122, v2
	v_mov_b32_e32 v123, v2
	v_mov_b32_e32 v124, v2
	v_mov_b32_e32 v125, v2
	v_mov_b32_e32 v126, v2
	v_mov_b32_e32 v127, v2
	v_mov_b32_e32 v128, v2
	v_mov_b32_e32 v129, v2
	s_nop 0
	s_nop 0
	s_nop 0
	s_nop 0
	s_nop 0
	s_nop 0
	s_nop 0
	s_nop 0
	s_nop 0
	s_nop 0
	s_nop 0
	s_nop 0
	s_nop 0
	s_nop 0
